# best plus 4-slot early-DMA rings in all hand-written attention loops (sel, MoBA, both window copies)
# baseline (speedup 1.0000x reference)
; #define MFMA32(a, b, c) __builtin_amdgcn_mfma_f32_32x32x16_bf16((a), (b), (c), 0, 0, 0)
; #define NEGINF (-__builtin_inff())
; DI int crow(int i, int h) { return (i & 3) + 8 * (i >> 2) + 4 * h; }
; template <class KP, class VP, class ACT, class FILL>
; DI void attn_loop(AttnSt& st, const bf16x8 (&qf)[4], int k0, int k1, size_t vstride, KP kp, VP vp, ACT act, FILL fill) {
;     ...
;   for (int kt = k0; kt <= k1; ++kt) {
;     const int kn = (kt < k1) ? kt + 1 : k1;
;     const int kn2 = (kt + 2 <= k1) ? kt + 2 : k1;
;     {
;       const bf16_t* v0 = vp(kn);
; #pragma unroll
;       for (int j = 0; j < 8; ++j) nxt.v[j] = *(const s16x4*)(v0 + 256 * j);
;     }
;     bf16x8 k2[4];
;     {
;       const bf16_t* krow = kp(kn2);
; #pragma unroll
;       for (int ss = 0; ss < 4; ++ss) k2[ss] = *(const bf16x8*)(krow + 512 * ss);
;     }
;     f32x16 s_next;
; #pragma unroll
;     for (int i = 0; i < 16; ++i) s_next[i] = 0.f;
; #pragma unroll
;     for (int ss = 0; ss < 4; ++ss) s_next = MFMA32(nxt.k[ss], qf[ss], s_next);
;     if (act(kt)) {
;       float lg[16];
;       fill(kt, s_cur, lg);
;       softmax_step_r(st, lg, cur);
; DI void nsa_win_item(const Params& p, int b, int head, int qb, const unsigned char* blut, const float* tbl) {
;     ...
;     attn_loop(st, qf, k0, qb, 32,
;       [&](int kt) { return K + (size_t)kt * 2048 + (h * 32 + r) * 8; },
;       [&](int kt) { return Vt + (size_t)kt * 2048 + (h * 32 + r) * 4; },
;       [&](int kt) { return true; },
;       [&](int kt, const f32x16& s, float (&lg)[16]) {
;         int dist[16]; float bv[16];
; #pragma unroll
;         for (int i = 0; i < 16; ++i) dist[i] = t - (kt * 32 + crow(i, h));
;         bias16(blut, tblh, dist, bv);
; #pragma unroll
;         for (int i = 0; i < 16; ++i) lg[i] = (dist[i] >= 0 && dist[i] < 512) ? s[i] + bv[i] : NEGINF;
.Lawin6_loop:
	s_lshr_b32 s23, s56, 1
	s_add_u32 s23, s23, 2
	s_add_u32 s61, s64, 0x8000
	s_sub_u32 s24, s61, 0x10000
	s_cmp_ge_u32 s61, 0x20000
	s_cselect_b32 s61, s24, s61
	s_lshr_b32 s24, s59, 1
	s_min_u32 s24, s23, s24
	s_lshl_b32 s26, s24, 13
	s_lshl_b32 s24, s58, 10
	s_add_u32 s26, s26, s24
	s_mov_b32 s27, 0
	v_lshl_add_u64 v[248:249], v[116:117], 0, s[26:27]
	v_lshl_add_u64 v[250:251], v[114:115], 0, s[26:27]
	v_add_co_u32_e32 v250, vcc, v250, v247
	v_addc_co_u32_e32 v251, vcc, 0, v251, vcc
	s_add_u32 s24, s24, s61
	s_mov_b32 m0, s24
	s_nop 0
	global_load_lds_dwordx4 v[248:249], off
	s_add_u32 s24, s24, 0x2000
	s_mov_b32 m0, s24
	s_nop 0
	global_load_lds_dwordx4 v[250:251], off
	s_waitcnt vmcnt(4)
	s_barrier
	s_cmp_le_u32 s56, s60
	s_cbranch_scc0 .Lawin6_skip
	s_add_u32 s24, s56, 1
	s_cmp_ge_u32 s24, s65
	s_cbranch_scc0 .Lawin6_skip
	v_lshl_add_u32 v248, v247, 1, s64
	ds_read_b128 v[80:83], v248 offset:0
	ds_read_b128 v[96:99], v248 offset:4096
	ds_read_b128 v[84:87], v248 offset:1024
	ds_read_b128 v[100:103], v248 offset:5120
	ds_read_b128 v[88:91], v248 offset:2048
	ds_read_b128 v[104:107], v248 offset:6144
	ds_read_b128 v[92:95], v248 offset:3072
	ds_read_b128 v[108:111], v248 offset:7168
	s_sub_i32 s61, s60, s56
	s_waitcnt lgkmcnt(6)
	v_mfma_f32_32x32x16_bf16 v[32:47], v[80:83], v[64:67], 0
	v_mfma_f32_32x32x16_bf16 v[48:63], v[96:99], v[64:67], 0
	s_waitcnt lgkmcnt(4)
	v_mfma_f32_32x32x16_bf16 v[32:47], v[84:87], v[68:71], v[32:47]
	v_mfma_f32_32x32x16_bf16 v[48:63], v[100:103], v[68:71], v[48:63]
	s_waitcnt lgkmcnt(2)
	v_mfma_f32_32x32x16_bf16 v[32:47], v[88:91], v[72:75], v[32:47]
	v_mfma_f32_32x32x16_bf16 v[48:63], v[104:107], v[72:75], v[48:63]
	s_waitcnt lgkmcnt(0)
	v_mfma_f32_32x32x16_bf16 v[32:47], v[92:95], v[76:79], v[32:47]
	v_mfma_f32_32x32x16_bf16 v[48:63], v[108:111], v[76:79], v[48:63]
	v_add_u32_e32 v250, s64, v247
	ds_read_b64 v[146:147], v250 offset:8192
	ds_read_b64 v[148:149], v250 offset:8704
	ds_read_b64 v[150:151], v250 offset:9216
	ds_read_b64 v[152:153], v250 offset:9728
	ds_read_b64 v[154:155], v250 offset:10240
	ds_read_b64 v[156:157], v250 offset:10752
	ds_read_b64 v[158:159], v250 offset:11264
	ds_read_b64 v[160:161], v250 offset:11776
	ds_read_b64 v[162:163], v250 offset:12288
	ds_read_b64 v[164:165], v250 offset:12800
	ds_read_b64 v[166:167], v250 offset:13312
	ds_read_b64 v[168:169], v250 offset:13824
	ds_read_b64 v[170:171], v250 offset:14336
	ds_read_b64 v[172:173], v250 offset:14848
	ds_read_b64 v[174:175], v250 offset:15360
	ds_read_b64 v[176:177], v250 offset:15872
	s_cmp_ge_i32 s61, 50
	s_cbranch_scc1 .Lawin6_far
	s_lshl_b32 s23, s61, 5
	v_add_u32_e32 v241, s23, v222
	v_lshl_add_u32 v244, v241, 2, v242
	v_subrev_u32_e32 v245, 128, v244
	ds_read_b32 v224, v244 offset:108
	ds_read_b32 v225, v244 offset:104
	ds_read_b32 v226, v244 offset:100
	ds_read_b32 v227, v244 offset:96
	ds_read_b32 v228, v244 offset:76
	ds_read_b32 v229, v244 offset:72
	ds_read_b32 v230, v244 offset:68
	ds_read_b32 v231, v244 offset:64
	ds_read_b32 v232, v244 offset:44
	ds_read_b32 v233, v244 offset:40
	ds_read_b32 v234, v244 offset:36
	ds_read_b32 v235, v244 offset:32
	ds_read_b32 v236, v244 offset:12
	ds_read_b32 v237, v244 offset:8
	ds_read_b32 v238, v244 offset:4
	ds_read_b32 v239, v244 offset:0
	s_waitcnt lgkmcnt(8)
	v_add_f32_e32 v32, v32, v224
	v_add_f32_e32 v33, v33, v225
	v_add_f32_e32 v34, v34, v226
	v_add_f32_e32 v35, v35, v227
	v_add_f32_e32 v36, v36, v228
	v_add_f32_e32 v37, v37, v229
	v_add_f32_e32 v38, v38, v230
	v_add_f32_e32 v39, v39, v231
	ds_read_b32 v224, v245 offset:108
	ds_read_b32 v225, v245 offset:104
	ds_read_b32 v226, v245 offset:100
	ds_read_b32 v227, v245 offset:96
	ds_read_b32 v228, v245 offset:76
	ds_read_b32 v229, v245 offset:72
	ds_read_b32 v230, v245 offset:68
	ds_read_b32 v231, v245 offset:64
	s_waitcnt lgkmcnt(8)
	v_add_f32_e32 v40, v40, v232
	v_add_f32_e32 v41, v41, v233
	v_add_f32_e32 v42, v42, v234
	v_add_f32_e32 v43, v43, v235
	v_add_f32_e32 v44, v44, v236
	v_add_f32_e32 v45, v45, v237
	v_add_f32_e32 v46, v46, v238
	v_add_f32_e32 v47, v47, v239
	ds_read_b32 v232, v245 offset:44
	ds_read_b32 v233, v245 offset:40
	ds_read_b32 v234, v245 offset:36
	ds_read_b32 v235, v245 offset:32
	ds_read_b32 v236, v245 offset:12
	ds_read_b32 v237, v245 offset:8
	ds_read_b32 v238, v245 offset:4
	ds_read_b32 v239, v245 offset:0
	s_waitcnt lgkmcnt(8)
	v_add_f32_e32 v48, v48, v224
	v_add_f32_e32 v49, v49, v225
	v_add_f32_e32 v50, v50, v226
	v_add_f32_e32 v51, v51, v227
	v_add_f32_e32 v52, v52, v228
	v_add_f32_e32 v53, v53, v229
	v_add_f32_e32 v54, v54, v230
	v_add_f32_e32 v55, v55, v231
	s_waitcnt lgkmcnt(0)
	v_add_f32_e32 v56, v56, v232
	v_add_f32_e32 v57, v57, v233
	v_add_f32_e32 v58, v58, v234
	v_add_f32_e32 v59, v59, v235
	v_add_f32_e32 v60, v60, v236
	v_add_f32_e32 v61, v61, v237
	v_add_f32_e32 v62, v62, v238
	v_add_f32_e32 v63, v63, v239
	s_cmp_ge_i32 s61, 15
	s_cbranch_scc0 .Lawin6_nowin
; #define NEGINF (-__builtin_inff())
; DI void nsa_win_item(const Params& p, int b, int head, int qb, const unsigned char* blut, const float* tbl) {
;     ...
;         for (int i = 0; i < 16; ++i) lg[i] = (dist[i] >= 0 && dist[i] < 512) ? s[i] + bv[i] : NEGINF;
	v_subrev_u32_e32 v246, 32, v241
	v_cmp_gt_i32_e32 vcc, 0x200, v241
	s_nop 1
	v_cndmask_b32_e32 v32, v199, v32, vcc
	v_cmp_gt_i32_e32 vcc, 0x201, v241
	s_nop 1
	v_cndmask_b32_e32 v33, v199, v33, vcc
	v_cmp_gt_i32_e32 vcc, 0x202, v241
	s_nop 1
	v_cndmask_b32_e32 v34, v199, v34, vcc
	v_cmp_gt_i32_e32 vcc, 0x203, v241
	s_nop 1
	v_cndmask_b32_e32 v35, v199, v35, vcc
	v_cmp_gt_i32_e32 vcc, 0x208, v241
	s_nop 1
	v_cndmask_b32_e32 v36, v199, v36, vcc
	v_cmp_gt_i32_e32 vcc, 0x209, v241
	s_nop 1
	v_cndmask_b32_e32 v37, v199, v37, vcc
	v_cmp_gt_i32_e32 vcc, 0x20a, v241
	s_nop 1
	v_cndmask_b32_e32 v38, v199, v38, vcc
	v_cmp_gt_i32_e32 vcc, 0x20b, v241
	s_nop 1
	v_cndmask_b32_e32 v39, v199, v39, vcc
	v_cmp_gt_i32_e32 vcc, 0x210, v241
	s_nop 1
	v_cndmask_b32_e32 v40, v199, v40, vcc
	v_cmp_gt_i32_e32 vcc, 0x211, v241
	s_nop 1
	v_cndmask_b32_e32 v41, v199, v41, vcc
	v_cmp_gt_i32_e32 vcc, 0x212, v241
	s_nop 1
	v_cndmask_b32_e32 v42, v199, v42, vcc
	v_cmp_gt_i32_e32 vcc, 0x213, v241
	s_nop 1
	v_cndmask_b32_e32 v43, v199, v43, vcc
	v_cmp_gt_i32_e32 vcc, 0x218, v241
	s_nop 1
	v_cndmask_b32_e32 v44, v199, v44, vcc
	v_cmp_gt_i32_e32 vcc, 0x219, v241
	s_nop 1
	v_cndmask_b32_e32 v45, v199, v45, vcc
	v_cmp_gt_i32_e32 vcc, 0x21a, v241
	s_nop 1
	v_cndmask_b32_e32 v46, v199, v46, vcc
	v_cmp_gt_i32_e32 vcc, 0x21b, v241
	s_nop 1
	v_cndmask_b32_e32 v47, v199, v47, vcc
	v_cmp_gt_i32_e32 vcc, 0x200, v246
	s_nop 1
	v_cndmask_b32_e32 v48, v199, v48, vcc
	v_cmp_gt_i32_e32 vcc, 0x201, v246
	s_nop 1
	v_cndmask_b32_e32 v49, v199, v49, vcc
	v_cmp_gt_i32_e32 vcc, 0x202, v246
	s_nop 1
	v_cndmask_b32_e32 v50, v199, v50, vcc
	v_cmp_gt_i32_e32 vcc, 0x203, v246
	s_nop 1
	v_cndmask_b32_e32 v51, v199, v51, vcc
	v_cmp_gt_i32_e32 vcc, 0x208, v246
	s_nop 1
	v_cndmask_b32_e32 v52, v199, v52, vcc
	v_cmp_gt_i32_e32 vcc, 0x209, v246
	s_nop 1
	v_cndmask_b32_e32 v53, v199, v53, vcc
	v_cmp_gt_i32_e32 vcc, 0x20a, v246
	s_nop 1
	v_cndmask_b32_e32 v54, v199, v54, vcc
	v_cmp_gt_i32_e32 vcc, 0x20b, v246
	s_nop 1
	v_cndmask_b32_e32 v55, v199, v55, vcc
	v_cmp_gt_i32_e32 vcc, 0x210, v246
	s_nop 1
	v_cndmask_b32_e32 v56, v199, v56, vcc
	v_cmp_gt_i32_e32 vcc, 0x211, v246
	s_nop 1
	v_cndmask_b32_e32 v57, v199, v57, vcc
	v_cmp_gt_i32_e32 vcc, 0x212, v246
	s_nop 1
	v_cndmask_b32_e32 v58, v199, v58, vcc
	v_cmp_gt_i32_e32 vcc, 0x213, v246
	s_nop 1
	v_cndmask_b32_e32 v59, v199, v59, vcc
	v_cmp_gt_i32_e32 vcc, 0x218, v246
	s_nop 1
	v_cndmask_b32_e32 v60, v199, v60, vcc
	v_cmp_gt_i32_e32 vcc, 0x219, v246
	s_nop 1
	v_cndmask_b32_e32 v61, v199, v61, vcc
	v_cmp_gt_i32_e32 vcc, 0x21a, v246
	s_nop 1
	v_cndmask_b32_e32 v62, v199, v62, vcc
	v_cmp_gt_i32_e32 vcc, 0x21b, v246
	s_nop 1
	v_cndmask_b32_e32 v63, v199, v63, vcc

; #define MFMA32(a, b, c) __builtin_amdgcn_mfma_f32_32x32x16_bf16((a), (b), (c), 0, 0, 0)
; #define NEGINF (-__builtin_inff())
; DI int crow(int i, int h) { return (i & 3) + 8 * (i >> 2) + 4 * h; }
; template <class KP, class VP, class ACT, class FILL>
; DI void attn_loop(AttnSt& st, const bf16x8 (&qf)[4], int k0, int k1, size_t vstride, KP kp, VP vp, ACT act, FILL fill) {
;     ...
;   for (int kt = k0; kt <= k1; ++kt) {
;     const int kn = (kt < k1) ? kt + 1 : k1;
;     const int kn2 = (kt + 2 <= k1) ? kt + 2 : k1;
;     {
;       const bf16_t* v0 = vp(kn);
; #pragma unroll
;       for (int j = 0; j < 8; ++j) nxt.v[j] = *(const s16x4*)(v0 + 256 * j);
;     }
;     bf16x8 k2[4];
;     {
;       const bf16_t* krow = kp(kn2);
; #pragma unroll
;       for (int ss = 0; ss < 4; ++ss) k2[ss] = *(const bf16x8*)(krow + 512 * ss);
;     }
;     f32x16 s_next;
; #pragma unroll
;     for (int i = 0; i < 16; ++i) s_next[i] = 0.f;
; #pragma unroll
;     for (int ss = 0; ss < 4; ++ss) s_next = MFMA32(nxt.k[ss], qf[ss], s_next);
;     if (act(kt)) {
;       float lg[16];
;       fill(kt, s_cur, lg);
;       softmax_step_r(st, lg, cur);
; DI void nsa_win_item(const Params& p, int b, int head, int qb, const unsigned char* blut, const float* tbl) {
;     ...
;     attn_loop(st, qf, k0, qb, 32,
;       [&](int kt) { return K + (size_t)kt * 2048 + (h * 32 + r) * 8; },
;       [&](int kt) { return Vt + (size_t)kt * 2048 + (h * 32 + r) * 4; },
;       [&](int kt) { return true; },
;       [&](int kt, const f32x16& s, float (&lg)[16]) {
;         int dist[16]; float bv[16];
; #pragma unroll
;         for (int i = 0; i < 16; ++i) dist[i] = t - (kt * 32 + crow(i, h));
;         bias16(blut, tblh, dist, bv);
; #pragma unroll
;         for (int i = 0; i < 16; ++i) lg[i] = (dist[i] >= 0 && dist[i] < 512) ? s[i] + bv[i] : NEGINF;
.Lawin4_loop:
	s_lshr_b32 s23, s56, 1
	s_add_u32 s23, s23, 2
	s_add_u32 s61, s64, 0x8000
	s_sub_u32 s24, s61, 0x10000
	s_cmp_ge_u32 s61, 0x20000
	s_cselect_b32 s61, s24, s61
	s_lshr_b32 s24, s59, 1
	s_min_u32 s24, s23, s24
	s_lshl_b32 s26, s24, 13
	s_lshl_b32 s24, s58, 10
	s_add_u32 s26, s26, s24
	s_mov_b32 s27, 0
	v_lshl_add_u64 v[186:187], v[116:117], 0, s[26:27]
	v_lshl_add_u64 v[126:127], v[114:115], 0, s[26:27]
	v_add_co_u32_e32 v126, vcc, v126, v185
	v_addc_co_u32_e32 v127, vcc, 0, v127, vcc
	s_add_u32 s24, s24, s61
	s_mov_b32 m0, s24
	s_nop 0
	global_load_lds_dwordx4 v[186:187], off
	s_add_u32 s24, s24, 0x2000
	s_mov_b32 m0, s24
	s_nop 0
	global_load_lds_dwordx4 v[126:127], off
	s_waitcnt vmcnt(4)
	s_barrier
	s_cmp_le_u32 s56, s60
	s_cbranch_scc0 .Lawin4_skip
	s_add_u32 s24, s56, 1
	s_cmp_ge_u32 s24, s65
	s_cbranch_scc0 .Lawin4_skip
	v_lshl_add_u32 v186, v185, 1, s64
	ds_read_b128 v[80:83], v186 offset:0
	ds_read_b128 v[96:99], v186 offset:4096
	ds_read_b128 v[84:87], v186 offset:1024
	ds_read_b128 v[100:103], v186 offset:5120
	ds_read_b128 v[88:91], v186 offset:2048
	ds_read_b128 v[104:107], v186 offset:6144
	ds_read_b128 v[92:95], v186 offset:3072
	ds_read_b128 v[108:111], v186 offset:7168
	s_sub_i32 s61, s60, s56
	s_waitcnt lgkmcnt(6)
	v_mfma_f32_32x32x16_bf16 v[32:47], v[80:83], v[64:67], 0
	v_mfma_f32_32x32x16_bf16 v[48:63], v[96:99], v[64:67], 0
	s_waitcnt lgkmcnt(4)
	v_mfma_f32_32x32x16_bf16 v[32:47], v[84:87], v[68:71], v[32:47]
	v_mfma_f32_32x32x16_bf16 v[48:63], v[100:103], v[68:71], v[48:63]
	s_waitcnt lgkmcnt(2)
	v_mfma_f32_32x32x16_bf16 v[32:47], v[88:91], v[72:75], v[32:47]
	v_mfma_f32_32x32x16_bf16 v[48:63], v[104:107], v[72:75], v[48:63]
	s_waitcnt lgkmcnt(0)
	v_mfma_f32_32x32x16_bf16 v[32:47], v[92:95], v[76:79], v[32:47]
	v_mfma_f32_32x32x16_bf16 v[48:63], v[108:111], v[76:79], v[48:63]
	v_add_u32_e32 v126, s64, v185
	ds_read_b64 v[146:147], v126 offset:8192
	ds_read_b64 v[148:149], v126 offset:8704
	ds_read_b64 v[150:151], v126 offset:9216
	ds_read_b64 v[152:153], v126 offset:9728
	ds_read_b64 v[154:155], v126 offset:10240
	ds_read_b64 v[156:157], v126 offset:10752
	ds_read_b64 v[158:159], v126 offset:11264
	ds_read_b64 v[160:161], v126 offset:11776
	ds_read_b64 v[162:163], v126 offset:12288
	ds_read_b64 v[164:165], v126 offset:12800
	ds_read_b64 v[166:167], v126 offset:13312
	ds_read_b64 v[168:169], v126 offset:13824
	ds_read_b64 v[170:171], v126 offset:14336
	ds_read_b64 v[172:173], v126 offset:14848
	ds_read_b64 v[174:175], v126 offset:15360
	ds_read_b64 v[176:177], v126 offset:15872
	s_cmp_ge_i32 s61, 50
	s_cbranch_scc1 .Lawin4_far
	s_lshl_b32 s23, s61, 5
	v_add_u32_e32 v179, s23, v142
	v_lshl_add_u32 v182, v179, 2, v180
	v_subrev_u32_e32 v183, 128, v182
	ds_read_b32 v118, v182 offset:108
	ds_read_b32 v119, v182 offset:104
	ds_read_b32 v120, v182 offset:100
	ds_read_b32 v121, v182 offset:96
	ds_read_b32 v122, v182 offset:76
	ds_read_b32 v123, v182 offset:72
	ds_read_b32 v124, v182 offset:68
	ds_read_b32 v125, v182 offset:64
	ds_read_b32 v132, v182 offset:44
	ds_read_b32 v133, v182 offset:40
	ds_read_b32 v134, v182 offset:36
	ds_read_b32 v135, v182 offset:32
	ds_read_b32 v218, v182 offset:12
	ds_read_b32 v219, v182 offset:8
	ds_read_b32 v220, v182 offset:4
	ds_read_b32 v221, v182 offset:0
	s_waitcnt lgkmcnt(8)
	v_add_f32_e32 v32, v32, v118
	v_add_f32_e32 v33, v33, v119
	v_add_f32_e32 v34, v34, v120
	v_add_f32_e32 v35, v35, v121
	v_add_f32_e32 v36, v36, v122
	v_add_f32_e32 v37, v37, v123
	v_add_f32_e32 v38, v38, v124
	v_add_f32_e32 v39, v39, v125
	ds_read_b32 v118, v183 offset:108
	ds_read_b32 v119, v183 offset:104
	ds_read_b32 v120, v183 offset:100
	ds_read_b32 v121, v183 offset:96
	ds_read_b32 v122, v183 offset:76
	ds_read_b32 v123, v183 offset:72
	ds_read_b32 v124, v183 offset:68
	ds_read_b32 v125, v183 offset:64
	s_waitcnt lgkmcnt(8)
	v_add_f32_e32 v40, v40, v132
	v_add_f32_e32 v41, v41, v133
	v_add_f32_e32 v42, v42, v134
	v_add_f32_e32 v43, v43, v135
	v_add_f32_e32 v44, v44, v218
	v_add_f32_e32 v45, v45, v219
	v_add_f32_e32 v46, v46, v220
	v_add_f32_e32 v47, v47, v221
	ds_read_b32 v132, v183 offset:44
	ds_read_b32 v133, v183 offset:40
	ds_read_b32 v134, v183 offset:36
	ds_read_b32 v135, v183 offset:32
	ds_read_b32 v218, v183 offset:12
	ds_read_b32 v219, v183 offset:8
	ds_read_b32 v220, v183 offset:4
	ds_read_b32 v221, v183 offset:0
	s_waitcnt lgkmcnt(8)
	v_add_f32_e32 v48, v48, v118
	v_add_f32_e32 v49, v49, v119
	v_add_f32_e32 v50, v50, v120
	v_add_f32_e32 v51, v51, v121
	v_add_f32_e32 v52, v52, v122
	v_add_f32_e32 v53, v53, v123
	v_add_f32_e32 v54, v54, v124
	v_add_f32_e32 v55, v55, v125
	s_waitcnt lgkmcnt(0)
	v_add_f32_e32 v56, v56, v132
	v_add_f32_e32 v57, v57, v133
	v_add_f32_e32 v58, v58, v134
	v_add_f32_e32 v59, v59, v135
	v_add_f32_e32 v60, v60, v218
	v_add_f32_e32 v61, v61, v219
	v_add_f32_e32 v62, v62, v220
	v_add_f32_e32 v63, v63, v221
	s_cmp_ge_i32 s61, 15
	s_cbranch_scc0 .Lawin4_nowin
; #define NEGINF (-__builtin_inff())
; DI void nsa_win_item(const Params& p, int b, int head, int qb, const unsigned char* blut, const float* tbl) {
;     ...
;         for (int i = 0; i < 16; ++i) lg[i] = (dist[i] >= 0 && dist[i] < 512) ? s[i] + bv[i] : NEGINF;
	v_subrev_u32_e32 v184, 32, v179
	v_cmp_gt_i32_e32 vcc, 0x200, v179
	s_nop 1
	v_cndmask_b32_e32 v32, v199, v32, vcc
	v_cmp_gt_i32_e32 vcc, 0x201, v179
	s_nop 1
	v_cndmask_b32_e32 v33, v199, v33, vcc
	v_cmp_gt_i32_e32 vcc, 0x202, v179
	s_nop 1
	v_cndmask_b32_e32 v34, v199, v34, vcc
	v_cmp_gt_i32_e32 vcc, 0x203, v179
	s_nop 1
	v_cndmask_b32_e32 v35, v199, v35, vcc
	v_cmp_gt_i32_e32 vcc, 0x208, v179
	s_nop 1
	v_cndmask_b32_e32 v36, v199, v36, vcc
	v_cmp_gt_i32_e32 vcc, 0x209, v179
	s_nop 1
	v_cndmask_b32_e32 v37, v199, v37, vcc
	v_cmp_gt_i32_e32 vcc, 0x20a, v179
	s_nop 1
	v_cndmask_b32_e32 v38, v199, v38, vcc
	v_cmp_gt_i32_e32 vcc, 0x20b, v179
	s_nop 1
	v_cndmask_b32_e32 v39, v199, v39, vcc
	v_cmp_gt_i32_e32 vcc, 0x210, v179
	s_nop 1
	v_cndmask_b32_e32 v40, v199, v40, vcc
	v_cmp_gt_i32_e32 vcc, 0x211, v179
	s_nop 1
	v_cndmask_b32_e32 v41, v199, v41, vcc
	v_cmp_gt_i32_e32 vcc, 0x212, v179
	s_nop 1
	v_cndmask_b32_e32 v42, v199, v42, vcc
	v_cmp_gt_i32_e32 vcc, 0x213, v179
	s_nop 1
	v_cndmask_b32_e32 v43, v199, v43, vcc
	v_cmp_gt_i32_e32 vcc, 0x218, v179
	s_nop 1
	v_cndmask_b32_e32 v44, v199, v44, vcc
	v_cmp_gt_i32_e32 vcc, 0x219, v179
	s_nop 1
	v_cndmask_b32_e32 v45, v199, v45, vcc
	v_cmp_gt_i32_e32 vcc, 0x21a, v179
	s_nop 1
	v_cndmask_b32_e32 v46, v199, v46, vcc
	v_cmp_gt_i32_e32 vcc, 0x21b, v179
	s_nop 1
	v_cndmask_b32_e32 v47, v199, v47, vcc
	v_cmp_gt_i32_e32 vcc, 0x200, v184
	s_nop 1
	v_cndmask_b32_e32 v48, v199, v48, vcc
	v_cmp_gt_i32_e32 vcc, 0x201, v184
	s_nop 1
	v_cndmask_b32_e32 v49, v199, v49, vcc
	v_cmp_gt_i32_e32 vcc, 0x202, v184
	s_nop 1
	v_cndmask_b32_e32 v50, v199, v50, vcc
	v_cmp_gt_i32_e32 vcc, 0x203, v184
	s_nop 1
	v_cndmask_b32_e32 v51, v199, v51, vcc
	v_cmp_gt_i32_e32 vcc, 0x208, v184
	s_nop 1
	v_cndmask_b32_e32 v52, v199, v52, vcc
	v_cmp_gt_i32_e32 vcc, 0x209, v184
	s_nop 1
	v_cndmask_b32_e32 v53, v199, v53, vcc
	v_cmp_gt_i32_e32 vcc, 0x20a, v184
	s_nop 1
	v_cndmask_b32_e32 v54, v199, v54, vcc
	v_cmp_gt_i32_e32 vcc, 0x20b, v184
	s_nop 1
	v_cndmask_b32_e32 v55, v199, v55, vcc
	v_cmp_gt_i32_e32 vcc, 0x210, v184
	s_nop 1
	v_cndmask_b32_e32 v56, v199, v56, vcc
	v_cmp_gt_i32_e32 vcc, 0x211, v184
	s_nop 1
	v_cndmask_b32_e32 v57, v199, v57, vcc
	v_cmp_gt_i32_e32 vcc, 0x212, v184
	s_nop 1
	v_cndmask_b32_e32 v58, v199, v58, vcc
	v_cmp_gt_i32_e32 vcc, 0x213, v184
	s_nop 1
	v_cndmask_b32_e32 v59, v199, v59, vcc
	v_cmp_gt_i32_e32 vcc, 0x218, v184
	s_nop 1
	v_cndmask_b32_e32 v60, v199, v60, vcc
	v_cmp_gt_i32_e32 vcc, 0x219, v184
	s_nop 1
	v_cndmask_b32_e32 v61, v199, v61, vcc
	v_cmp_gt_i32_e32 vcc, 0x21a, v184
	s_nop 1
	v_cndmask_b32_e32 v62, v199, v62, vcc
	v_cmp_gt_i32_e32 vcc, 0x21b, v184
	s_nop 1
	v_cndmask_b32_e32 v63, v199, v63, vcc
